# projection->attention barrier becomes a 32-workgroup batch-class barrier; censuses taken before the first grid barrier
# speedup vs baseline: 1.0265x; 1.0032x over previous
; #define LAS __attribute__((address_space(3)))
; __device__ __forceinline__ unsigned xb_add(unsigned* p, unsigned v) { return __hip_atomic_fetch_add(p, v, __ATOMIC_RELAXED, __HIP_MEMORY_SCOPE_AGENT); }
; __device__ __forceinline__ unsigned xb_xcc_id() { return (unsigned)__builtin_amdgcn_s_getreg((3 << 11) | 20) & 0xFu; }
; __device__ __forceinline__ XcdBarrier xcd_barrier_post(unsigned* bar, volatile LAS unsigned* st) {
;     XcdBarrier b; b.bar = bar; b.x = xb_xcc_id(); b.st = st;
;     if (threadIdx.x == 0) (void)xb_add(&bar[XB_XCNT(b.x)], 1u);
;     return b;
; }
; __device__ __forceinline__ void xcd_barrier(const XcdBarrier& b) {
;     asm volatile("s_waitcnt vmcnt(0)" ::: "memory");
;     __syncthreads();
;     if (threadIdx.x == 0) {
;         unsigned* bar = b.bar;
;         __builtin_amdgcn_s_waitcnt(0);
;         unsigned nloc = b.st[0], nx = b.st[1];
;         if (nloc == 0u) { xcd_barrier_complete(bar, b.x, nloc, nx); b.st[0] = nloc; b.st[1] = nx; }
;         const unsigned old = xb_add(&bar[XB_XSUB(b.x)], 1u);
.LBB0_101:
	s_cmp_lt_i32 s19, 2
	s_cbranch_scc1 .LBB0_155
	s_waitcnt vmcnt(0)
	s_waitcnt lgkmcnt(0)
	s_barrier
	s_mov_b64 s[0:1], exec
	v_readlane_b32 s2, v247, 37
	v_readlane_b32 s3, v247, 38
	s_and_b64 s[2:3], s[0:1], s[2:3]
	s_mov_b64 exec, s[2:3]
	s_cbranch_execz .LBB0_154
	v_readlane_b32 s4, v247, 36
	s_nop 0
	s_and_b32 s2, s4, 7
	s_lshl_b32 s2, s2, 2
	s_lshl_b32 s3, 1, s2
	v_mov_b32_e32 v2, s3
	s_and_b32 s2, s90, 31
	s_lshl_b32 s2, s2, 6
	s_add_u32 s2, s62, s2
	s_addc_u32 s3, s63, 0
	s_add_u32 s2, s2, 0xa000
	s_addc_u32 s3, s3, 0
	v_mov_b32_e32 v1, 0
	global_atomic_add v1, v2, s[2:3]
	s_and_b32 s2, s4, 3
	s_lshl_b32 s2, s2, 3
	s_lshl_b32 s3, 1, s2
	v_mov_b32_e32 v2, s3
	s_and_b32 s2, s90, 7
	s_lshl_b32 s2, s2, 7
	s_lshr_b32 s3, s4, 2
	s_and_b32 s3, s3, 1
	s_lshl_b32 s3, s3, 6
	s_add_i32 s2, s2, s3
	s_add_u32 s2, s62, s2
	s_addc_u32 s3, s63, 0
	s_add_u32 s2, s2, 0xa800
	s_addc_u32 s3, s3, 0
	global_atomic_add v1, v2, s[2:3]
	s_add_i32 s2, 0, 0x24160
	v_mov_b32_e32 v1, s2
	s_waitcnt vmcnt(0) expcnt(0) lgkmcnt(0)
	ds_read_b32 v3, v1
	s_add_i32 s2, 0, 0x24164
	v_mov_b32_e32 v1, s2
	ds_read_b32 v1, v1
	s_waitcnt lgkmcnt(1)
	v_cmp_ne_u32_e32 vcc, 0, v3
	s_cbranch_vccnz .LBB0_118
	v_readlane_b32 s2, v247, 0
	v_readlane_b32 s3, v247, 1
	s_load_dwordx2 s[6:7], s[2:3], 0x4
	s_add_u32 s2, s62, 0x4200
	s_addc_u32 s3, s63, 0
	s_add_u32 s4, s62, 0x4400
	s_addc_u32 s5, s63, 0
	s_waitcnt lgkmcnt(0)
	s_mul_i32 s33, s6, s80
	s_add_u32 s6, s62, 0x4500
	s_mul_i32 s33, s33, s7
	s_addc_u32 s7, s63, 0
	s_add_u32 s8, s62, 0x4600
	s_addc_u32 s9, s63, 0
	s_add_u32 s10, s62, 0x4700
	s_addc_u32 s11, s63, 0
	s_add_u32 s12, s62, 0x4800
	s_addc_u32 s13, s63, 0
	s_add_u32 s14, s62, 0x4900
	s_addc_u32 s15, s63, 0
	s_add_u32 s16, s62, 0x4a00
	s_addc_u32 s17, s63, 0
	s_add_u32 s18, s62, 0x4b00
	s_addc_u32 s19, s63, 0
	s_add_u32 s20, s62, 0x4c00
	s_addc_u32 s21, s63, 0
	s_add_u32 s24, s62, 0x4d00
	s_addc_u32 s25, s63, 0
	s_add_u32 s26, s62, 0x4e00
	s_addc_u32 s27, s63, 0
	s_add_u32 s28, s62, 0x4f00
	s_addc_u32 s29, s63, 0
	s_add_u32 s30, s62, 0x5000
	s_addc_u32 s31, s63, 0
	s_add_u32 s34, s62, 0x5100
	s_addc_u32 s35, s63, 0
	s_add_u32 s36, s62, 0x5200
	s_addc_u32 s37, s63, 0
	s_add_u32 s38, s62, 0x5300
	s_addc_u32 s39, s63, 0
	s_mov_b32 s48, 1
	v_mov_b32_e32 v17, 0
	s_branch .LBB0_106

; __device__ __forceinline__ unsigned xb_ld(unsigned* p)              { return __hip_atomic_load(p, __ATOMIC_RELAXED, __HIP_MEMORY_SCOPE_AGENT); }
; __device__ __forceinline__ unsigned xb_add(unsigned* p, unsigned v) { return __hip_atomic_fetch_add(p, v, __ATOMIC_RELAXED, __HIP_MEMORY_SCOPE_AGENT); }
; #define XB_SPIN(cond, bar) do { unsigned _sp = 0; while (cond) { __builtin_amdgcn_s_sleep(1); \
;     if ((++_sp & 255u) == 0u) { if (xb_ld(&(bar)[XB_TMO])) break; if (_sp > XB_SPIN_CAP) { atomicAdd(&(bar)[XB_TMO], 1u); break; } } } } while (0)
; __device__ __forceinline__ void xcd_barrier(const XcdBarrier& b) {
;     asm volatile("s_waitcnt vmcnt(0)" ::: "memory");
;     __syncthreads();
;     if (threadIdx.x == 0) {
;         unsigned* bar = b.bar;
;         __builtin_amdgcn_s_waitcnt(0);
;         unsigned nloc = b.st[0], nx = b.st[1];
;         if (nloc == 0u) { xcd_barrier_complete(bar, b.x, nloc, nx); b.st[0] = nloc; b.st[1] = nx; }
;         const unsigned old = xb_add(&bar[XB_XSUB(b.x)], 1u);
;         const unsigned gen = old / nloc;
;         if (old + 1u == (gen + 1u) * nloc) {
;             __builtin_amdgcn_fence(__ATOMIC_RELEASE, "agent");
;             asm volatile("s_waitcnt vmcnt(0)" ::: "memory");
;             const unsigned og = xb_add(&bar[XB_TOP], 1u);
;             const unsigned tg = og / nx;
;             if (og + 1u == (tg + 1u) * nx) xb_add(&bar[XB_TOPGEN], 1u);
;             else XB_SPIN(xb_ld(&bar[XB_TOPGEN]) == tg, bar);
;             __builtin_amdgcn_fence(__ATOMIC_ACQUIRE, "agent");
;             xb_add(&bar[XB_XGEN(b.x)], 1u);
;             asm volatile("s_waitcnt vmcnt(0)" ::: "memory");
;         } else {
;             XB_SPIN(xb_ld(&bar[XB_XGEN(b.x)]) == gen, bar);
;             __builtin_amdgcn_fence(__ATOMIC_ACQUIRE, "agent");
;             asm volatile("s_waitcnt vmcnt(0)" ::: "memory");
;         }
;     }
;     __syncthreads();
; }
.LBB0_322:
	s_waitcnt vmcnt(0)
	s_waitcnt vmcnt(0) lgkmcnt(0)
	s_barrier
	s_mov_b64 s[0:1], exec
	v_readlane_b32 s2, v247, 37
	v_readlane_b32 s3, v247, 38
	s_and_b64 s[2:3], s[0:1], s[2:3]
	s_mov_b64 exec, s[2:3]
	s_cbranch_execz .LBB0_374
	v_readlane_b32 s5, v247, 36
	s_and_b32 s2, s90, 7
	s_lshl_b32 s2, s2, 7
	s_add_u32 s2, s62, s2
	s_addc_u32 s3, s63, 0
	s_lshr_b32 s6, s5, 2
	s_and_b32 s6, s6, 1
	s_lshl_b32 s6, s6, 6
	s_add_u32 s6, s2, s6
	s_addc_u32 s7, s3, 0
	s_add_u32 s6, s6, 0xa800
	s_addc_u32 s7, s7, 0
	s_add_u32 s2, s2, 0xe000
	s_addc_u32 s3, s3, 0
	s_and_b32 s5, s5, 3
	s_lshl_b32 s5, s5, 3
	s_lshl_b32 s5, 32, s5
	v_mov_b32_e32 v1, 0
	global_load_dword v3, v1, s[6:7] sc1
	v_mov_b32_e32 v2, 1
	s_mov_b32 s4, 0
	s_waitcnt vmcnt(0) lgkmcnt(0)
	v_cmp_eq_u32_e32 vcc, s5, v3
	s_cbranch_vccnz .Lgrpbar3_same
	buffer_wbl2 sc1
	s_waitcnt vmcnt(0)

; __device__ __forceinline__ unsigned xb_ld(unsigned* p)              { return __hip_atomic_load(p, __ATOMIC_RELAXED, __HIP_MEMORY_SCOPE_AGENT); }
; #define XB_SPIN(cond, bar) do { unsigned _sp = 0; while (cond) { __builtin_amdgcn_s_sleep(1); \
;     if ((++_sp & 255u) == 0u) { if (xb_ld(&(bar)[XB_TMO])) break; if (_sp > XB_SPIN_CAP) { atomicAdd(&(bar)[XB_TMO], 1u); break; } } } } while (0)
; __device__ __forceinline__ void xcd_barrier(const XcdBarrier& b) {
;     ...
;             XB_SPIN(xb_ld(&bar[XB_XGEN(b.x)]) == gen, bar);
;             __builtin_amdgcn_fence(__ATOMIC_ACQUIRE, "agent");
.Lgrpbar3_spin:
	global_load_dword v3, v1, s[2:3] sc1
	s_waitcnt vmcnt(0)
	v_cmp_lt_u32_e32 vcc, 31, v3
	s_cbranch_vccnz .Lgrpbar3_done
	s_sleep 1
	s_add_i32 s4, s4, 1
	s_cmp_lt_u32 s4, 0x200000
	s_cbranch_scc1 .Lgrpbar3_spin
